# rows phases 6 and 9: loop-invariant gain vectors (g_post_mix, g_pre_ffn, g_post_ffn) loaded once before the row loop instead of after every store; removes 46 full vmcnt(0) drains per loop iteration
# speedup vs baseline: 1.0067x; 1.0067x over previous
.LBB0_30:
	s_mov_b64 s[14:15], 0
	s_andn2_b64 vcc, exec, s[4:5]
	s_mov_b64 s[12:13], 0
	s_cbranch_vccnz .LBB0_79
	v_readlane_b32 s0, v248, 31
	s_cmp_gt_i32 s0, 7
	s_cbranch_scc0 .LBB0_51
	s_cmp_gt_i32 s0, 8
	s_cbranch_scc0 .LBB0_52
	s_cmp_eq_u32 s0, 9
	s_mov_b64 s[12:13], -1
	s_cbranch_scc0 .LBB0_54
	v_ashrrev_i32_e32 v0, 6, v200
	v_readlane_b32 s0, v251, 5
	s_waitcnt vmcnt(0)
	s_nop 0
	v_add_u32_e32 v64, s0, v0
	v_cmp_gt_i32_e32 vcc, s33, v64
	s_and_saveexec_b64 s[12:13], vcc
	s_cbranch_execz .LBB0_53
	v_add_u32_e32 v0, 64, v220
	v_xor_b32_e32 v1, 32, v219
	v_cmp_lt_i32_e64 s[4:5], v1, v0
	v_and_b32_e32 v4, 63, v200
	v_readlane_b32 s72, v250, 53
	v_cndmask_b32_e64 v1, v219, v1, s[4:5]
	v_lshlrev_b32_e32 v122, 2, v1
	v_xor_b32_e32 v1, 16, v219
	v_cmp_lt_i32_e64 s[4:5], v1, v0
	v_readlane_b32 s74, v250, 55
	v_readlane_b32 s75, v250, 56
	v_cndmask_b32_e64 v1, v219, v1, s[4:5]
	v_lshlrev_b32_e32 v123, 2, v1
	v_xor_b32_e32 v1, 8, v219
	v_cmp_lt_i32_e64 s[4:5], v1, v0
	v_mov_b32_e32 v3, v197
	s_load_dword s25, s[54:55], 0x0
	v_cndmask_b32_e64 v1, v219, v1, s[4:5]
	v_lshlrev_b32_e32 v124, 2, v1
	v_xor_b32_e32 v1, 4, v219
	v_cmp_lt_i32_e64 s[4:5], v1, v0
	v_ashrrev_i32_e32 v65, 31, v64
	v_cmp_gt_u32_e32 vcc, 16, v4
	v_cndmask_b32_e64 v1, v219, v1, s[4:5]
	v_lshlrev_b32_e32 v125, 2, v1
	v_xor_b32_e32 v1, 2, v219
	v_cmp_lt_i32_e64 s[4:5], v1, v0
	v_lshlrev_b32_e32 v196, 2, v4
	v_readlane_b32 s0, v250, 51
	v_cndmask_b32_e64 v1, v219, v1, s[4:5]
	v_lshlrev_b32_e32 v126, 2, v1
	v_xor_b32_e32 v1, 1, v219
	v_cmp_lt_i32_e64 s[4:5], v1, v0
	v_readlane_b32 s1, v250, 52
	s_waitcnt lgkmcnt(0)
	s_lshl_b32 s16, s25, 4
	v_cndmask_b32_e64 v0, v219, v1, s[4:5]
	v_lshlrev_b32_e32 v127, 2, v0
	v_lshlrev_b32_e32 v0, 4, v4
	v_or_b32_e32 v2, 0x400, v0
	v_lshl_add_u64 v[72:73], s[74:75], 0, v[2:3]
	v_or_b32_e32 v2, 0x800, v0
	v_lshl_add_u64 v[74:75], s[74:75], 0, v[2:3]
	v_or_b32_e32 v2, 0xc00, v0
	v_lshl_add_u64 v[76:77], s[74:75], 0, v[2:3]
	v_lshlrev_b32_e32 v2, 3, v4
	v_lshlrev_b64 v[4:5], 6, v[64:65]
	v_lshl_add_u64 v[4:5], v[4:5], 0, v[196:197]
	v_readlane_b32 s4, v250, 43
	v_lshl_add_u64 v[80:81], s[66:67], 0, v[4:5]
	v_lshlrev_b64 v[4:5], 11, v[64:65]
	v_readlane_b32 s10, v250, 49
	v_readlane_b32 s11, v250, 50
	v_or_b32_e32 v4, v4, v2
	v_lshl_add_u64 v[82:83], s[0:1], 0, v[4:5]
	v_lshl_add_u64 v[78:79], s[10:11], 0, v[2:3]
	v_lshlrev_b64 v[2:3], 12, v[64:65]
	v_readlane_b32 s0, v249, 5
	v_mov_b32_e32 v1, v197
	v_readlane_b32 s73, v250, 54
	s_ashr_i32 s17, s16, 31
	v_or_b32_e32 v2, v2, v0
	v_readlane_b32 s1, v249, 6
	s_lshl_b32 s2, s25, 2
	v_lshl_add_u64 v[66:67], s[66:67], 0, v[196:197]
	v_lshl_add_u64 v[68:69], s[72:73], 0, v[0:1]
	global_load_dwordx4 v[152:155], v[68:69], off
	global_load_dwordx4 v[156:159], v[68:69], off offset:1024
	global_load_dwordx4 v[160:163], v[68:69], off offset:2048
	global_load_dwordx4 v[166:169], v[68:69], off offset:3072
	v_lshl_add_u64 v[70:71], s[74:75], 0, v[0:1]
	s_lshl_b32 s24, s25, 3
	s_mul_i32 s25, s25, 12
	s_lshl_b64 s[18:19], s[16:17], 6
	s_lshl_b64 s[20:21], s[16:17], 11
	v_lshl_add_u64 v[84:85], s[0:1], 0, v[2:3]
	s_lshl_b64 s[22:23], s[16:17], 12
	s_mov_b64 s[30:31], 0
	v_readlane_b32 s76, v250, 57
	v_readlane_b32 s77, v250, 58
	v_readlane_b32 s78, v250, 59
	v_readlane_b32 s79, v250, 60
	v_readlane_b32 s80, v250, 61
	v_readlane_b32 s81, v250, 62
	v_readlane_b32 s82, v250, 63
	v_readlane_b32 s83, v249, 0
	v_readlane_b32 s84, v249, 1
	v_readlane_b32 s85, v249, 2
	v_readlane_b32 s86, v249, 3
	v_readlane_b32 s87, v249, 4
	v_readlane_b32 s5, v250, 44
	v_readlane_b32 s6, v250, 45
	v_readlane_b32 s7, v250, 46
	v_readlane_b32 s8, v250, 47
	v_readlane_b32 s9, v250, 48
	s_branch .LBB0_37

.LBB0_45:
	s_or_b64 exec, exec, s[10:11]
	s_waitcnt vmcnt(0)
	ds_bpermute_b32 v5, v122, v4
	v_lshlrev_b32_e32 v132, 16, v0
	v_and_b32_e32 v133, 0xffff0000, v0
	v_lshlrev_b32_e32 v134, 16, v1
	v_and_b32_e32 v135, 0xffff0000, v1
	s_waitcnt lgkmcnt(0)
	v_add_f32_e32 v4, v4, v5
	ds_bpermute_b32 v5, v123, v4
	s_waitcnt lgkmcnt(0)
	v_add_f32_e32 v4, v4, v5
	ds_bpermute_b32 v5, v124, v4
	s_waitcnt lgkmcnt(0)
	v_add_f32_e32 v6, v4, v5
	ds_bpermute_b32 v7, v125, v6
	v_lshlrev_b64 v[4:5], 12, v[2:3]
	v_lshlrev_b64 v[2:3], 11, v[2:3]
	v_lshl_add_u64 v[0:1], v[70:71], 0, v[4:5]
	v_lshl_add_u64 v[86:87], v[78:79], 0, v[2:3]
	s_waitcnt lgkmcnt(0)
	v_add_f32_e32 v6, v6, v7
	ds_bpermute_b32 v7, v126, v6
	s_waitcnt lgkmcnt(0)
	v_add_f32_e32 v88, v6, v7
	ds_bpermute_b32 v89, v127, v88
	global_load_dwordx4 v[12:15], v[0:1], off nt
	global_load_dwordx4 v[8:11], v[0:1], off offset:1024 nt
	global_load_dwordx4 v[4:7], v[0:1], off offset:2048 nt
	s_nop 0
	global_load_dwordx4 v[0:3], v[0:1], off offset:3072 nt
	s_waitcnt lgkmcnt(0)
	v_add_f32_e32 v88, v88, v89
	v_fmamk_f32 v88, v88, 0x3a800000, v198
	v_mul_f32_e32 v89, 0x4b800000, v88
	v_cmp_gt_f32_e64 s[10:11], s51, v88
	s_nop 1
	v_cndmask_b32_e64 v88, v88, v89, s[10:11]
	v_rsq_f32_e32 v113, v88
	global_load_dwordx2 v[96:97], v[86:87], off nt
	global_load_dwordx2 v[90:91], v[86:87], off offset:512 nt
	global_load_dwordx2 v[88:89], v[86:87], off offset:1024 nt
	s_nop 0
	global_load_dwordx2 v[86:87], v[86:87], off offset:1536 nt
	v_mul_f32_e32 v136, 0x45800000, v113
	v_cndmask_b32_e64 v136, v113, v136, s[10:11]
	v_pk_mul_f32 v[132:133], v[136:137], v[132:133] op_sel_hi:[0,1]
	v_pk_mul_f32 v[134:135], v[136:137], v[134:135] op_sel_hi:[0,1]
	v_pk_fma_f32 v[60:61], v[152:153], v[132:133], v[60:61]
	v_pk_fma_f32 v[62:63], v[154:155], v[134:135], v[62:63]
	global_store_dwordx4 v[84:85], v[60:63], off offset:-3072 nt
	v_lshlrev_b32_e32 v128, 16, v120
	v_and_b32_e32 v129, 0xffff0000, v120
	v_lshlrev_b32_e32 v120, 16, v121
	v_and_b32_e32 v121, 0xffff0000, v121
	v_pk_mul_f32 v[128:129], v[136:137], v[128:129] op_sel_hi:[0,1]
	v_pk_mul_f32 v[120:121], v[136:137], v[120:121] op_sel_hi:[0,1]
	v_pk_fma_f32 v[56:57], v[156:157], v[128:129], v[56:57]
	v_pk_fma_f32 v[58:59], v[120:121], v[158:159], v[58:59]
	global_store_dwordx4 v[84:85], v[56:59], off offset:-2048 nt
	v_lshlrev_b32_e32 v60, 16, v118
	v_and_b32_e32 v61, 0xffff0000, v118
	v_lshlrev_b32_e32 v62, 16, v119
	v_and_b32_e32 v63, 0xffff0000, v119
	v_pk_mul_f32 v[60:61], v[136:137], v[60:61] op_sel_hi:[0,1]
	v_pk_mul_f32 v[62:63], v[136:137], v[62:63] op_sel_hi:[0,1]
	v_pk_fma_f32 v[52:53], v[60:61], v[160:161], v[52:53]
	v_pk_fma_f32 v[54:55], v[62:63], v[162:163], v[54:55]
	global_store_dwordx4 v[84:85], v[52:55], off offset:-1024 nt
	v_lshlrev_b32_e32 v56, 16, v116
	v_and_b32_e32 v57, 0xffff0000, v116
	v_lshlrev_b32_e32 v58, 16, v117
	v_and_b32_e32 v59, 0xffff0000, v117
	v_pk_mul_f32 v[56:57], v[136:137], v[56:57] op_sel_hi:[0,1]
	v_pk_mul_f32 v[58:59], v[136:137], v[58:59] op_sel_hi:[0,1]
	v_pk_fma_f32 v[48:49], v[56:57], v[166:167], v[48:49]
	v_pk_fma_f32 v[50:51], v[58:59], v[168:169], v[50:51]
	global_store_dwordx4 v[84:85], v[48:51], off nt
	s_and_saveexec_b64 s[10:11], s[8:9]
	s_cbranch_execnz .LBB0_48
	s_or_b64 exec, exec, s[10:11]
	s_and_saveexec_b64 s[8:9], s[6:7]
	s_cbranch_execnz .LBB0_49

.LBB0_48:
	ds_bpermute_b32 v48, v122, v103
	v_lshlrev_b32_e32 v56, 16, v114
	v_and_b32_e32 v57, 0xffff0000, v114
	v_ashrrev_i32_e32 v113, 31, v112
	v_lshlrev_b32_e32 v58, 16, v115
	s_waitcnt lgkmcnt(0)
	v_add_f32_e32 v48, v103, v48
	ds_bpermute_b32 v49, v123, v48
	v_and_b32_e32 v59, 0xffff0000, v115
	s_waitcnt lgkmcnt(0)
	v_add_f32_e32 v48, v48, v49
	ds_bpermute_b32 v49, v124, v48
	s_waitcnt lgkmcnt(0)
	v_add_f32_e32 v48, v48, v49
	ds_bpermute_b32 v49, v125, v48
	s_waitcnt lgkmcnt(0)
	v_add_f32_e32 v48, v48, v49
	ds_bpermute_b32 v49, v126, v48
	s_waitcnt lgkmcnt(0)
	v_add_f32_e32 v48, v48, v49
	ds_bpermute_b32 v49, v127, v48
	s_waitcnt lgkmcnt(0)
	v_add_f32_e32 v48, v48, v49
	v_fmamk_f32 v48, v48, 0x3a800000, v198
	v_cmp_gt_f32_e64 s[8:9], s51, v48
	v_mul_f32_e32 v49, 0x4b800000, v48
	s_nop 0
	v_cndmask_b32_e64 v48, v48, v49, s[8:9]
	v_rsq_f32_e32 v48, v48
	s_nop 0
	v_mul_f32_e32 v49, 0x45800000, v48
	v_cndmask_b32_e64 v50, v48, v49, s[8:9]
	v_pk_mul_f32 v[56:57], v[50:51], v[56:57] op_sel_hi:[0,1]
	v_lshlrev_b64 v[48:49], 12, v[112:113]
	v_pk_fma_f32 v[44:45], v[152:153], v[56:57], v[44:45]
	v_pk_mul_f32 v[52:53], v[50:51], v[58:59] op_sel_hi:[0,1]
	v_pk_fma_f32 v[46:47], v[154:155], v[52:53], v[46:47]
	v_lshl_add_u64 v[52:53], v[70:71], 0, v[48:49]
	global_store_dwordx4 v[52:53], v[44:47], off nt
	v_lshlrev_b32_e32 v52, 16, v110
	v_and_b32_e32 v53, 0xffff0000, v110
	v_lshlrev_b32_e32 v54, 16, v111
	v_and_b32_e32 v55, 0xffff0000, v111
	v_pk_mul_f32 v[52:53], v[50:51], v[52:53] op_sel_hi:[0,1]
	v_pk_mul_f32 v[54:55], v[50:51], v[54:55] op_sel_hi:[0,1]
	v_lshl_add_u64 v[56:57], v[72:73], 0, v[48:49]
	v_pk_fma_f32 v[40:41], v[156:157], v[52:53], v[40:41]
	v_pk_fma_f32 v[42:43], v[54:55], v[158:159], v[42:43]
	global_store_dwordx4 v[56:57], v[40:43], off nt
	v_lshlrev_b32_e32 v44, 16, v108
	v_and_b32_e32 v45, 0xffff0000, v108
	v_lshlrev_b32_e32 v46, 16, v109
	v_and_b32_e32 v47, 0xffff0000, v109
	v_pk_mul_f32 v[44:45], v[50:51], v[44:45] op_sel_hi:[0,1]
	v_pk_fma_f32 v[36:37], v[44:45], v[160:161], v[36:37]
	v_pk_mul_f32 v[40:41], v[50:51], v[46:47] op_sel_hi:[0,1]
	v_pk_fma_f32 v[38:39], v[40:41], v[162:163], v[38:39]
	v_lshl_add_u64 v[40:41], v[74:75], 0, v[48:49]
	global_store_dwordx4 v[40:41], v[36:39], off nt
	v_lshlrev_b32_e32 v40, 16, v106
	v_and_b32_e32 v41, 0xffff0000, v106
	v_lshlrev_b32_e32 v42, 16, v107
	v_and_b32_e32 v43, 0xffff0000, v107
	v_pk_mul_f32 v[40:41], v[50:51], v[40:41] op_sel_hi:[0,1]
	v_pk_fma_f32 v[32:33], v[40:41], v[166:167], v[32:33]
	v_pk_mul_f32 v[36:37], v[50:51], v[42:43] op_sel_hi:[0,1]
	v_pk_fma_f32 v[34:35], v[36:37], v[168:169], v[34:35]
	v_lshl_add_u64 v[36:37], v[76:77], 0, v[48:49]
	global_store_dwordx4 v[36:37], v[32:35], off nt
	s_or_b64 exec, exec, s[10:11]
	s_and_saveexec_b64 s[8:9], s[6:7]
	s_cbranch_execz .LBB0_47
.LBB0_49:
	ds_bpermute_b32 v32, v122, v93
	v_lshlrev_b32_e32 v40, 16, v104
	v_and_b32_e32 v41, 0xffff0000, v104
	v_ashrrev_i32_e32 v103, 31, v102
	v_lshlrev_b32_e32 v42, 16, v105
	s_waitcnt lgkmcnt(0)
	v_add_f32_e32 v32, v93, v32
	ds_bpermute_b32 v33, v123, v32
	v_and_b32_e32 v43, 0xffff0000, v105
	s_waitcnt lgkmcnt(0)
	v_add_f32_e32 v32, v32, v33
	ds_bpermute_b32 v33, v124, v32
	s_waitcnt lgkmcnt(0)
	v_add_f32_e32 v32, v32, v33
	ds_bpermute_b32 v33, v125, v32
	s_waitcnt lgkmcnt(0)
	v_add_f32_e32 v32, v32, v33
	ds_bpermute_b32 v33, v126, v32
	s_waitcnt lgkmcnt(0)
	v_add_f32_e32 v32, v32, v33
	ds_bpermute_b32 v33, v127, v32
	s_waitcnt lgkmcnt(0)
	v_add_f32_e32 v32, v32, v33
	v_fmamk_f32 v32, v32, 0x3a800000, v198
	v_cmp_gt_f32_e64 s[6:7], s51, v32
	v_mul_f32_e32 v33, 0x4b800000, v32
	s_nop 0
	v_cndmask_b32_e64 v32, v32, v33, s[6:7]
	v_rsq_f32_e32 v32, v32
	s_nop 0
	v_mul_f32_e32 v33, 0x45800000, v32
	v_cndmask_b32_e64 v34, v32, v33, s[6:7]
	v_pk_mul_f32 v[40:41], v[34:35], v[40:41] op_sel_hi:[0,1]
	v_lshlrev_b64 v[32:33], 12, v[102:103]
	v_pk_fma_f32 v[28:29], v[152:153], v[40:41], v[28:29]
	v_pk_mul_f32 v[36:37], v[34:35], v[42:43] op_sel_hi:[0,1]
	v_pk_fma_f32 v[30:31], v[154:155], v[36:37], v[30:31]
	v_lshl_add_u64 v[36:37], v[70:71], 0, v[32:33]
	global_store_dwordx4 v[36:37], v[28:31], off nt
	v_lshlrev_b32_e32 v36, 16, v100
	v_and_b32_e32 v37, 0xffff0000, v100
	v_lshlrev_b32_e32 v38, 16, v101
	v_and_b32_e32 v39, 0xffff0000, v101
	v_pk_mul_f32 v[36:37], v[34:35], v[36:37] op_sel_hi:[0,1]
	v_pk_mul_f32 v[38:39], v[34:35], v[38:39] op_sel_hi:[0,1]
	v_lshl_add_u64 v[40:41], v[72:73], 0, v[32:33]
	v_pk_fma_f32 v[24:25], v[156:157], v[36:37], v[24:25]
	v_pk_fma_f32 v[26:27], v[38:39], v[158:159], v[26:27]
	global_store_dwordx4 v[40:41], v[24:27], off nt
	v_lshlrev_b32_e32 v28, 16, v98
	v_and_b32_e32 v29, 0xffff0000, v98
	v_lshlrev_b32_e32 v30, 16, v99
	v_and_b32_e32 v31, 0xffff0000, v99
	v_pk_mul_f32 v[28:29], v[34:35], v[28:29] op_sel_hi:[0,1]
	v_pk_fma_f32 v[20:21], v[28:29], v[160:161], v[20:21]
	v_pk_mul_f32 v[24:25], v[34:35], v[30:31] op_sel_hi:[0,1]
	v_pk_fma_f32 v[22:23], v[24:25], v[162:163], v[22:23]
	v_lshl_add_u64 v[24:25], v[74:75], 0, v[32:33]
	global_store_dwordx4 v[24:25], v[20:23], off nt
	v_lshlrev_b32_e32 v24, 16, v94
	v_and_b32_e32 v25, 0xffff0000, v94
	v_lshlrev_b32_e32 v26, 16, v95
	v_and_b32_e32 v27, 0xffff0000, v95
	v_pk_mul_f32 v[24:25], v[34:35], v[24:25] op_sel_hi:[0,1]
	v_pk_fma_f32 v[16:17], v[24:25], v[166:167], v[16:17]
	v_pk_mul_f32 v[20:21], v[34:35], v[26:27] op_sel_hi:[0,1]
	v_pk_fma_f32 v[18:19], v[20:21], v[168:169], v[18:19]
	v_lshl_add_u64 v[20:21], v[76:77], 0, v[32:33]
	global_store_dwordx4 v[20:21], v[16:19], off nt
	s_or_b64 exec, exec, s[8:9]
	s_and_saveexec_b64 s[6:7], s[4:5]
	s_cbranch_execz .LBB0_36
.LBB0_50:
	s_waitcnt vmcnt(0)
	ds_bpermute_b32 v16, v122, v65
	v_lshlrev_b32_e32 v24, 16, v96
	v_and_b32_e32 v25, 0xffff0000, v96
	v_ashrrev_i32_e32 v93, 31, v92
	v_lshlrev_b32_e32 v26, 16, v97
	s_waitcnt lgkmcnt(0)
	v_add_f32_e32 v16, v65, v16
	ds_bpermute_b32 v17, v123, v16
	v_and_b32_e32 v27, 0xffff0000, v97
	s_waitcnt lgkmcnt(0)
	v_add_f32_e32 v16, v16, v17
	ds_bpermute_b32 v17, v124, v16
	s_waitcnt lgkmcnt(0)
	v_add_f32_e32 v16, v16, v17
	ds_bpermute_b32 v17, v125, v16
	s_waitcnt lgkmcnt(0)
	v_add_f32_e32 v16, v16, v17
	ds_bpermute_b32 v17, v126, v16
	s_waitcnt lgkmcnt(0)
	v_add_f32_e32 v16, v16, v17
	ds_bpermute_b32 v17, v127, v16
	s_waitcnt lgkmcnt(0)
	v_add_f32_e32 v16, v16, v17
	v_fmamk_f32 v16, v16, 0x3a800000, v198
	v_cmp_gt_f32_e64 s[4:5], s51, v16
	v_mul_f32_e32 v17, 0x4b800000, v16
	s_nop 0
	v_cndmask_b32_e64 v16, v16, v17, s[4:5]
	v_rsq_f32_e32 v16, v16
	s_nop 0
	v_mul_f32_e32 v17, 0x45800000, v16
	v_cndmask_b32_e64 v18, v16, v17, s[4:5]
	v_pk_mul_f32 v[24:25], v[18:19], v[24:25] op_sel_hi:[0,1]
	v_lshlrev_b64 v[16:17], 12, v[92:93]
	v_pk_fma_f32 v[12:13], v[152:153], v[24:25], v[12:13]
	v_pk_mul_f32 v[20:21], v[18:19], v[26:27] op_sel_hi:[0,1]
	v_pk_fma_f32 v[14:15], v[154:155], v[20:21], v[14:15]
	v_lshl_add_u64 v[20:21], v[70:71], 0, v[16:17]
	global_store_dwordx4 v[20:21], v[12:15], off nt
	v_lshlrev_b32_e32 v20, 16, v90
	v_and_b32_e32 v21, 0xffff0000, v90
	v_lshlrev_b32_e32 v22, 16, v91
	v_and_b32_e32 v23, 0xffff0000, v91
	v_pk_mul_f32 v[20:21], v[18:19], v[20:21] op_sel_hi:[0,1]
	v_pk_mul_f32 v[22:23], v[18:19], v[22:23] op_sel_hi:[0,1]
	v_lshl_add_u64 v[24:25], v[72:73], 0, v[16:17]
	v_pk_fma_f32 v[8:9], v[156:157], v[20:21], v[8:9]
	v_pk_fma_f32 v[10:11], v[22:23], v[158:159], v[10:11]
	global_store_dwordx4 v[24:25], v[8:11], off nt
	v_lshlrev_b32_e32 v12, 16, v88
	v_and_b32_e32 v13, 0xffff0000, v88
	v_lshlrev_b32_e32 v14, 16, v89
	v_and_b32_e32 v15, 0xffff0000, v89
	v_pk_mul_f32 v[12:13], v[18:19], v[12:13] op_sel_hi:[0,1]
	v_pk_fma_f32 v[4:5], v[12:13], v[160:161], v[4:5]
	v_pk_mul_f32 v[8:9], v[18:19], v[14:15] op_sel_hi:[0,1]
	v_pk_fma_f32 v[6:7], v[8:9], v[162:163], v[6:7]
	v_lshl_add_u64 v[8:9], v[74:75], 0, v[16:17]
	global_store_dwordx4 v[8:9], v[4:7], off nt
	v_lshlrev_b32_e32 v8, 16, v86
	v_and_b32_e32 v9, 0xffff0000, v86
	v_lshlrev_b32_e32 v10, 16, v87
	v_and_b32_e32 v11, 0xffff0000, v87
	v_pk_mul_f32 v[8:9], v[18:19], v[8:9] op_sel_hi:[0,1]
	v_pk_fma_f32 v[0:1], v[8:9], v[166:167], v[0:1]
	v_pk_mul_f32 v[4:5], v[18:19], v[10:11] op_sel_hi:[0,1]
	v_pk_fma_f32 v[2:3], v[4:5], v[168:169], v[2:3]
	v_lshl_add_u64 v[4:5], v[76:77], 0, v[16:17]
	global_store_dwordx4 v[4:5], v[0:3], off nt
	s_branch .LBB0_36

.LBB0_79:
	s_and_b64 vcc, exec, s[14:15]
	s_cbranch_vccz .LBB0_100
	v_readlane_b32 s0, v248, 31
	s_cmp_gt_i32 s0, 3
	s_mov_b64 s[4:5], -1
	s_cbranch_scc0 .LBB0_132
	v_readlane_b32 s0, v248, 31
	s_cmp_lt_i32 s0, 5
	s_mov_b64 s[0:1], -1
	s_cbranch_scc1 .LBB0_119
	v_readlane_b32 s0, v248, 31
	s_cmp_gt_i32 s0, 5
	s_mov_b64 s[0:1], -1
	s_cbranch_scc0 .LBB0_102
	v_ashrrev_i32_e32 v0, 6, v200
	v_readlane_b32 s0, v251, 5
	s_waitcnt vmcnt(0)
	s_nop 0
	v_add_u32_e32 v64, s0, v0
	v_cmp_gt_i32_e32 vcc, s33, v64
	s_and_saveexec_b64 s[14:15], vcc
	s_cbranch_execz .LBB0_101
	v_add_u32_e32 v3, 64, v220
	v_xor_b32_e32 v4, 32, v219
	v_cmp_lt_i32_e64 s[4:5], v4, v3
	s_load_dword s25, s[54:55], 0x0
	v_and_b32_e32 v2, 63, v200
	v_cndmask_b32_e64 v4, v219, v4, s[4:5]
	v_lshlrev_b32_e32 v124, 2, v4
	v_xor_b32_e32 v4, 16, v219
	v_cmp_lt_i32_e64 s[4:5], v4, v3
	v_ashrrev_i32_e32 v65, 31, v64
	v_lshlrev_b32_e32 v0, 2, v2
	v_cndmask_b32_e64 v4, v219, v4, s[4:5]
	v_lshlrev_b32_e32 v125, 2, v4
	v_xor_b32_e32 v4, 8, v219
	v_cmp_lt_i32_e64 s[4:5], v4, v3
	v_mov_b32_e32 v1, v197
	v_lshlrev_b32_e32 v196, 4, v2
	v_cndmask_b32_e64 v4, v219, v4, s[4:5]
	v_lshlrev_b32_e32 v126, 2, v4
	v_xor_b32_e32 v4, 4, v219
	v_cmp_lt_i32_e64 s[4:5], v4, v3
	s_waitcnt lgkmcnt(0)
	s_lshl_b32 s16, s25, 4
	v_lshl_add_u64 v[66:67], s[66:67], 0, v[0:1]
	v_cndmask_b32_e64 v4, v219, v4, s[4:5]
	v_lshlrev_b32_e32 v127, 2, v4
	v_xor_b32_e32 v4, 2, v219
	v_cmp_lt_i32_e64 s[4:5], v4, v3
	v_readlane_b32 s72, v250, 53
	v_readlane_b32 s20, v249, 27
	v_cndmask_b32_e64 v4, v219, v4, s[4:5]
	v_lshlrev_b32_e32 v128, 2, v4
	v_xor_b32_e32 v4, 1, v219
	v_cmp_lt_i32_e64 s[4:5], v4, v3
	v_cmp_gt_u32_e32 vcc, 16, v2
	v_readlane_b32 s74, v250, 55
	v_cndmask_b32_e64 v3, v219, v4, s[4:5]
	v_readlane_b32 s4, v249, 31
	v_readlane_b32 s5, v249, 32
	v_readlane_b32 s6, v249, 33
	v_readlane_b32 s7, v249, 34
	v_lshlrev_b64 v[4:5], 6, v[64:65]
	v_lshl_add_u64 v[68:69], s[4:5], 0, v[196:197]
	v_lshl_add_u64 v[72:73], s[6:7], 0, v[196:197]
	global_load_dwordx4 v[142:145], v[68:69], off
	global_load_dwordx4 v[146:149], v[68:69], off offset:1024
	global_load_dwordx4 v[152:155], v[68:69], off offset:2048
	global_load_dwordx4 v[156:159], v[68:69], off offset:3072
	global_load_dwordx4 v[160:163], v[72:73], off
	global_load_dwordx4 v[166:169], v[72:73], off offset:1024
	global_load_dwordx4 v[170:173], v[72:73], off offset:2048
	global_load_dwordx4 v[174:177], v[72:73], off offset:3072
	v_readlane_b32 s4, v250, 43
	v_lshl_add_u64 v[0:1], v[4:5], 0, v[0:1]
	v_lshlrev_b32_e32 v129, 2, v3
	v_readlane_b32 s75, v250, 56
	v_readlane_b32 s78, v250, 59
	v_readlane_b32 s79, v250, 60
	v_lshlrev_b32_e32 v2, 3, v2
	v_mov_b32_e32 v3, v197
	v_readlane_b32 s21, v249, 28
	v_readlane_b32 s22, v249, 29
	v_readlane_b32 s23, v249, 30
	v_readlane_b32 s8, v250, 47
	v_readlane_b32 s9, v250, 48
	v_lshl_add_u64 v[80:81], s[66:67], 0, v[0:1]
	s_ashr_i32 s17, s16, 31
	v_lshlrev_b64 v[0:1], 12, v[64:65]
	v_lshlrev_b64 v[84:85], 11, v[64:65]
	s_lshl_b32 s2, s25, 2
	v_lshl_add_u64 v[70:71], s[74:75], 0, v[196:197]
	v_lshl_add_u64 v[74:75], s[78:79], 0, v[2:3]
	v_lshl_add_u64 v[76:77], s[20:21], 0, v[196:197]
	v_lshl_add_u64 v[78:79], s[8:9], 0, v[2:3]
	s_lshl_b32 s24, s25, 3
	s_mul_i32 s25, s25, 12
	s_lshl_b64 s[18:19], s[16:17], 6
	v_lshl_add_u64 v[82:83], s[20:21], 0, v[0:1]
	s_lshl_b64 s[20:21], s[16:17], 12
	v_or_b32_e32 v84, v84, v2
	s_lshl_b64 s[22:23], s[16:17], 11
	v_lshl_add_u64 v[86:87], s[74:75], 0, v[0:1]
	s_mov_b64 s[30:31], 0
	v_readlane_b32 s73, v250, 54
	v_readlane_b32 s76, v250, 57
	v_readlane_b32 s77, v250, 58
	v_readlane_b32 s80, v250, 61
	v_readlane_b32 s81, v250, 62
	v_readlane_b32 s82, v250, 63
	v_readlane_b32 s83, v249, 0
	v_readlane_b32 s84, v249, 1
	v_readlane_b32 s85, v249, 2
	v_readlane_b32 s86, v249, 3
	v_readlane_b32 s87, v249, 4
	v_readlane_b32 s5, v250, 44
	v_readlane_b32 s6, v250, 45
	v_readlane_b32 s7, v250, 46
	v_readlane_b32 s10, v250, 49
	v_readlane_b32 s11, v250, 50
	s_branch .LBB0_86

.LBB0_94:
	s_or_b64 exec, exec, s[10:11]
	s_waitcnt vmcnt(0)
	ds_bpermute_b32 v5, v124, v4
	v_lshlrev_b32_e32 v134, 16, v0
	v_and_b32_e32 v135, 0xffff0000, v0
	v_lshlrev_b32_e32 v136, 16, v1
	v_and_b32_e32 v137, 0xffff0000, v1
	s_waitcnt lgkmcnt(0)
	v_add_f32_e32 v4, v4, v5
	ds_bpermute_b32 v5, v125, v4
	v_lshl_add_u64 v[138:139], v[86:87], 0, v[196:197]
	v_readlane_b32 s72, v250, 53
	v_readlane_b32 s78, v250, 59
	v_readlane_b32 s79, v250, 60
	s_waitcnt lgkmcnt(0)
	v_add_f32_e32 v6, v4, v5
	ds_bpermute_b32 v7, v126, v6
	v_lshlrev_b64 v[4:5], 12, v[2:3]
	v_lshlrev_b64 v[2:3], 11, v[2:3]
	v_lshl_add_u64 v[0:1], v[76:77], 0, v[4:5]
	v_lshl_add_u64 v[90:91], v[78:79], 0, v[2:3]
	s_waitcnt lgkmcnt(0)
	v_add_f32_e32 v6, v6, v7
	ds_bpermute_b32 v7, v127, v6
	v_readlane_b32 s73, v250, 54
	v_readlane_b32 s74, v250, 55
	v_readlane_b32 s75, v250, 56
	v_readlane_b32 s76, v250, 57
	s_waitcnt lgkmcnt(0)
	v_add_f32_e32 v6, v6, v7
	ds_bpermute_b32 v7, v128, v6
	v_readlane_b32 s77, v250, 58
	v_readlane_b32 s80, v250, 61
	v_readlane_b32 s81, v250, 62
	v_readlane_b32 s82, v250, 63
	s_waitcnt lgkmcnt(0)
	v_add_f32_e32 v92, v6, v7
	ds_bpermute_b32 v93, v129, v92
	global_load_dwordx4 v[12:15], v[0:1], off nt
	global_load_dwordx4 v[8:11], v[0:1], off offset:1024 nt
	global_load_dwordx4 v[4:7], v[0:1], off offset:2048 nt
	s_nop 0
	global_load_dwordx4 v[0:3], v[0:1], off offset:3072 nt
	v_readlane_b32 s83, v249, 0
	v_readlane_b32 s84, v249, 1
	v_readlane_b32 s85, v249, 2
	s_waitcnt lgkmcnt(0)
	v_add_f32_e32 v92, v92, v93
	v_fmamk_f32 v92, v92, 0x3a800000, v198
	v_mul_f32_e32 v93, 0x4b800000, v92
	v_cmp_gt_f32_e64 s[10:11], s51, v92
	v_readlane_b32 s86, v249, 3
	v_readlane_b32 s87, v249, 4
	v_cndmask_b32_e64 v92, v92, v93, s[10:11]
	v_rsq_f32_e32 v109, v92
	global_load_dwordx2 v[98:99], v[90:91], off nt
	global_load_dwordx2 v[94:95], v[90:91], off offset:512 nt
	global_load_dwordx2 v[92:93], v[90:91], off offset:1024 nt
	s_nop 0
	global_load_dwordx2 v[90:91], v[90:91], off offset:1536 nt
	v_mul_f32_e32 v140, 0x45800000, v109
	v_cndmask_b32_e64 v140, v109, v140, s[10:11]
	v_pk_mul_f32 v[134:135], v[140:141], v[134:135] op_sel_hi:[0,1]
	v_pk_mul_f32 v[136:137], v[140:141], v[136:137] op_sel_hi:[0,1]
	v_pk_fma_f32 v[60:61], v[142:143], v[134:135], v[60:61]
	v_pk_fma_f32 v[62:63], v[144:145], v[136:137], v[62:63]
	global_store_dwordx4 v[138:139], v[60:63], off
	v_lshlrev_b32_e32 v134, 16, v122
	v_and_b32_e32 v135, 0xffff0000, v122
	v_lshlrev_b32_e32 v122, 16, v123
	v_and_b32_e32 v123, 0xffff0000, v123
	v_pk_mul_f32 v[134:135], v[140:141], v[134:135] op_sel_hi:[0,1]
	v_pk_mul_f32 v[122:123], v[140:141], v[122:123] op_sel_hi:[0,1]
	v_pk_fma_f32 v[56:57], v[134:135], v[146:147], v[56:57]
	v_pk_fma_f32 v[58:59], v[122:123], v[148:149], v[58:59]
	global_store_dwordx4 v[138:139], v[56:59], off offset:1024
	v_lshlrev_b32_e32 v122, 16, v120
	v_and_b32_e32 v123, 0xffff0000, v120
	v_lshlrev_b32_e32 v120, 16, v121
	v_and_b32_e32 v121, 0xffff0000, v121
	v_pk_mul_f32 v[122:123], v[140:141], v[122:123] op_sel_hi:[0,1]
	v_pk_mul_f32 v[120:121], v[140:141], v[120:121] op_sel_hi:[0,1]
	v_mov_b32_e32 v134, v63
	v_mov_b32_e32 v135, v59
	v_pk_fma_f32 v[52:53], v[122:123], v[152:153], v[52:53]
	v_pk_fma_f32 v[54:55], v[120:121], v[154:155], v[54:55]
	global_store_dwordx4 v[138:139], v[52:55], off offset:2048
	v_lshlrev_b32_e32 v130, 16, v118
	v_and_b32_e32 v131, 0xffff0000, v118
	v_lshlrev_b32_e32 v118, 16, v119
	v_and_b32_e32 v119, 0xffff0000, v119
	v_pk_mul_f32 v[130:131], v[140:141], v[130:131] op_sel_hi:[0,1]
	v_pk_mul_f32 v[118:119], v[140:141], v[118:119] op_sel_hi:[0,1]
	v_mov_b32_e32 v132, v62
	v_mov_b32_e32 v133, v58
	v_pk_fma_f32 v[48:49], v[130:131], v[156:157], v[48:49]
	v_pk_fma_f32 v[50:51], v[118:119], v[158:159], v[50:51]
	global_store_dwordx4 v[138:139], v[48:51], off offset:3072
	v_mov_b32_e32 v130, v61
	v_mov_b32_e32 v131, v57
	v_mov_b32_e32 v122, v60
	v_mov_b32_e32 v123, v56
	v_pk_mul_f32 v[130:131], v[130:131], v[130:131]
	s_nop 0
	v_pk_fma_f32 v[122:123], v[122:123], v[122:123], v[130:131]
	v_mov_b32_e32 v130, v53
	v_pk_fma_f32 v[122:123], v[132:133], v[132:133], v[122:123]
	v_mov_b32_e32 v131, v49
	v_pk_fma_f32 v[122:123], v[134:135], v[134:135], v[122:123]
	v_pk_mul_f32 v[130:131], v[130:131], v[130:131]
	v_add_f32_e32 v109, v122, v123
	v_mov_b32_e32 v122, v52
	v_mov_b32_e32 v123, v48
	v_mov_b32_e32 v132, v54
	v_mov_b32_e32 v133, v50
	v_pk_fma_f32 v[122:123], v[122:123], v[122:123], v[130:131]
	v_mov_b32_e32 v134, v55
	v_mov_b32_e32 v135, v51
	v_pk_fma_f32 v[122:123], v[132:133], v[132:133], v[122:123]
	s_nop 0
	v_pk_fma_f32 v[122:123], v[134:135], v[134:135], v[122:123]
	s_nop 0
	v_add_f32_e32 v109, v109, v122
	v_add_f32_e32 v109, v109, v123
	ds_bpermute_b32 v122, v124, v109
	s_waitcnt lgkmcnt(0)
	v_add_f32_e32 v109, v109, v122
	ds_bpermute_b32 v122, v125, v109
	s_waitcnt lgkmcnt(0)
	v_add_f32_e32 v109, v109, v122
	ds_bpermute_b32 v122, v126, v109
	s_waitcnt lgkmcnt(0)
	v_add_f32_e32 v109, v109, v122
	ds_bpermute_b32 v122, v127, v109
	s_waitcnt lgkmcnt(0)
	v_add_f32_e32 v109, v109, v122
	ds_bpermute_b32 v122, v128, v109
	s_waitcnt lgkmcnt(0)
	v_add_f32_e32 v109, v109, v122
	ds_bpermute_b32 v122, v129, v109
	s_waitcnt lgkmcnt(0)
	v_add_f32_e32 v109, v109, v122
	v_fmamk_f32 v109, v109, 0x3a800000, v198
	v_mul_f32_e32 v122, 0x4b800000, v109
	v_cmp_gt_f32_e64 s[10:11], s51, v109
	s_nop 1
	v_cndmask_b32_e64 v109, v109, v122, s[10:11]
	v_rsq_f32_e32 v109, v109
	v_lshl_add_u64 v[122:123], s[78:79], 0, v[84:85]
	v_mul_f32_e32 v130, 0x45800000, v109
	v_cndmask_b32_e64 v130, v109, v130, s[10:11]
	v_pk_mul_f32 v[60:61], v[60:61], v[130:131] op_sel_hi:[1,0]
	v_pk_mul_f32 v[62:63], v[62:63], v[130:131] op_sel_hi:[1,0]
	v_pk_mul_f32 v[56:57], v[56:57], v[130:131] op_sel_hi:[1,0]
	v_pk_mul_f32 v[58:59], v[58:59], v[130:131] op_sel_hi:[1,0]
	v_pk_mul_f32 v[52:53], v[52:53], v[130:131] op_sel_hi:[1,0]
	v_pk_mul_f32 v[60:61], v[160:161], v[60:61]
	v_pk_mul_f32 v[62:63], v[162:163], v[62:63]
	v_cvt_pk_bf16_f32 v60, v60, v61
	v_cvt_pk_bf16_f32 v61, v62, v63
	global_store_dwordx2 v[122:123], v[60:61], off
	v_pk_mul_f32 v[54:55], v[54:55], v[130:131] op_sel_hi:[1,0]
	v_pk_mul_f32 v[48:49], v[48:49], v[130:131] op_sel_hi:[1,0]
	v_pk_mul_f32 v[50:51], v[50:51], v[130:131] op_sel_hi:[1,0]
	v_pk_mul_f32 v[56:57], v[166:167], v[56:57]
	v_pk_mul_f32 v[58:59], v[58:59], v[168:169]
	v_cvt_pk_bf16_f32 v56, v56, v57
	v_cvt_pk_bf16_f32 v57, v58, v59
	global_store_dwordx2 v[122:123], v[56:57], off offset:512
	v_pk_mul_f32 v[52:53], v[52:53], v[170:171]
	v_pk_mul_f32 v[54:55], v[54:55], v[172:173]
	v_cvt_pk_bf16_f32 v52, v52, v53
	v_cvt_pk_bf16_f32 v53, v54, v55
	global_store_dwordx2 v[122:123], v[52:53], off offset:1024
	v_pk_mul_f32 v[48:49], v[48:49], v[174:175]
	v_pk_mul_f32 v[50:51], v[50:51], v[176:177]
	v_cvt_pk_bf16_f32 v48, v48, v49
	v_cvt_pk_bf16_f32 v49, v50, v51
	global_store_dwordx2 v[122:123], v[48:49], off offset:1536
	s_and_saveexec_b64 s[10:11], s[8:9]
	s_cbranch_execnz .LBB0_97
	s_or_b64 exec, exec, s[10:11]
	s_and_saveexec_b64 s[8:9], s[6:7]
	s_cbranch_execnz .LBB0_98

.LBB0_97:
	ds_bpermute_b32 v52, v124, v97
	v_ashrrev_i32_e32 v109, 31, v108
	v_lshlrev_b32_e32 v54, 16, v117
	s_waitcnt lgkmcnt(0)
	v_add_f32_e32 v52, v97, v52
	ds_bpermute_b32 v53, v125, v52
	s_waitcnt lgkmcnt(0)
	v_add_f32_e32 v52, v52, v53
	ds_bpermute_b32 v53, v126, v52
	s_waitcnt lgkmcnt(0)
	v_add_f32_e32 v52, v52, v53
	ds_bpermute_b32 v53, v127, v52
	s_waitcnt lgkmcnt(0)
	v_add_f32_e32 v52, v52, v53
	ds_bpermute_b32 v53, v128, v52
	s_waitcnt lgkmcnt(0)
	v_add_f32_e32 v55, v52, v53
	ds_bpermute_b32 v56, v129, v55
	v_lshlrev_b32_e32 v52, 16, v116
	v_and_b32_e32 v53, 0xffff0000, v116
	s_waitcnt lgkmcnt(0)
	v_add_f32_e32 v55, v55, v56
	v_fmamk_f32 v55, v55, 0x3a800000, v198
	v_mul_f32_e32 v56, 0x4b800000, v55
	v_cmp_gt_f32_e64 s[8:9], s51, v55
	s_nop 1
	v_cndmask_b32_e64 v55, v55, v56, s[8:9]
	v_rsq_f32_e32 v58, v55
	v_and_b32_e32 v55, 0xffff0000, v117
	v_lshlrev_b64 v[56:57], 12, v[108:109]
	v_lshl_add_u64 v[56:57], v[70:71], 0, v[56:57]
	v_mul_f32_e32 v59, 0x45800000, v58
	v_cndmask_b32_e64 v58, v58, v59, s[8:9]
	v_pk_mul_f32 v[52:53], v[58:59], v[52:53] op_sel_hi:[0,1]
	v_pk_mul_f32 v[54:55], v[58:59], v[54:55] op_sel_hi:[0,1]
	v_pk_fma_f32 v[44:45], v[142:143], v[52:53], v[44:45]
	v_pk_fma_f32 v[46:47], v[144:145], v[54:55], v[46:47]
	global_store_dwordx4 v[56:57], v[44:47], off
	v_lshlrev_b32_e32 v52, 16, v114
	v_and_b32_e32 v53, 0xffff0000, v114
	v_lshlrev_b32_e32 v54, 16, v115
	v_and_b32_e32 v55, 0xffff0000, v115
	v_pk_mul_f32 v[52:53], v[58:59], v[52:53] op_sel_hi:[0,1]
	v_pk_mul_f32 v[54:55], v[58:59], v[54:55] op_sel_hi:[0,1]
	v_pk_fma_f32 v[40:41], v[52:53], v[146:147], v[40:41]
	v_pk_fma_f32 v[42:43], v[54:55], v[148:149], v[42:43]
	global_store_dwordx4 v[56:57], v[40:43], off offset:1024
	v_lshlrev_b32_e32 v52, 16, v112
	v_and_b32_e32 v53, 0xffff0000, v112
	v_lshlrev_b32_e32 v54, 16, v113
	v_and_b32_e32 v55, 0xffff0000, v113
	v_pk_mul_f32 v[52:53], v[58:59], v[52:53] op_sel_hi:[0,1]
	v_pk_mul_f32 v[54:55], v[58:59], v[54:55] op_sel_hi:[0,1]
	v_pk_fma_f32 v[36:37], v[52:53], v[152:153], v[36:37]
	v_pk_fma_f32 v[38:39], v[54:55], v[154:155], v[38:39]
	global_store_dwordx4 v[56:57], v[36:39], off offset:2048
	v_lshlrev_b32_e32 v52, 16, v110
	v_and_b32_e32 v53, 0xffff0000, v110
	v_lshlrev_b32_e32 v54, 16, v111
	v_and_b32_e32 v55, 0xffff0000, v111
	v_pk_mul_f32 v[52:53], v[58:59], v[52:53] op_sel_hi:[0,1]
	v_pk_mul_f32 v[54:55], v[58:59], v[54:55] op_sel_hi:[0,1]
	v_mov_b32_e32 v58, v47
	v_mov_b32_e32 v59, v43
	v_pk_fma_f32 v[32:33], v[52:53], v[156:157], v[32:33]
	v_pk_fma_f32 v[34:35], v[54:55], v[158:159], v[34:35]
	global_store_dwordx4 v[56:57], v[32:35], off offset:3072
	v_mov_b32_e32 v54, v45
	v_mov_b32_e32 v55, v41
	v_mov_b32_e32 v52, v44
	v_mov_b32_e32 v53, v40
	v_pk_mul_f32 v[54:55], v[54:55], v[54:55]
	v_mov_b32_e32 v56, v46
	v_mov_b32_e32 v57, v42
	v_pk_fma_f32 v[52:53], v[52:53], v[52:53], v[54:55]
	v_mov_b32_e32 v54, v37
	v_pk_fma_f32 v[52:53], v[56:57], v[56:57], v[52:53]
	v_mov_b32_e32 v55, v33
	v_pk_fma_f32 v[52:53], v[58:59], v[58:59], v[52:53]
	v_pk_mul_f32 v[54:55], v[54:55], v[54:55]
	v_add_f32_e32 v60, v52, v53
	v_mov_b32_e32 v52, v36
	v_mov_b32_e32 v53, v32
	v_mov_b32_e32 v56, v38
	v_mov_b32_e32 v57, v34
	v_pk_fma_f32 v[52:53], v[52:53], v[52:53], v[54:55]
	v_mov_b32_e32 v58, v39
	v_mov_b32_e32 v59, v35
	v_pk_fma_f32 v[52:53], v[56:57], v[56:57], v[52:53]
	s_nop 0
	v_pk_fma_f32 v[52:53], v[58:59], v[58:59], v[52:53]
	s_nop 0
	v_add_f32_e32 v52, v60, v52
	v_add_f32_e32 v52, v52, v53
	ds_bpermute_b32 v53, v124, v52
	s_waitcnt lgkmcnt(0)
	v_add_f32_e32 v52, v52, v53
	ds_bpermute_b32 v53, v125, v52
	s_waitcnt lgkmcnt(0)
	v_add_f32_e32 v52, v52, v53
	ds_bpermute_b32 v53, v126, v52
	s_waitcnt lgkmcnt(0)
	v_add_f32_e32 v52, v52, v53
	ds_bpermute_b32 v53, v127, v52
	s_waitcnt lgkmcnt(0)
	v_add_f32_e32 v52, v52, v53
	ds_bpermute_b32 v53, v128, v52
	s_waitcnt lgkmcnt(0)
	v_add_f32_e32 v52, v52, v53
	ds_bpermute_b32 v53, v129, v52
	s_waitcnt lgkmcnt(0)
	v_add_f32_e32 v52, v52, v53
	v_fmamk_f32 v52, v52, 0x3a800000, v198
	v_mul_f32_e32 v53, 0x4b800000, v52
	v_cmp_gt_f32_e64 s[8:9], s51, v52
	s_nop 1
	v_cndmask_b32_e64 v52, v52, v53, s[8:9]
	v_rsq_f32_e32 v54, v52
	v_lshlrev_b64 v[52:53], 11, v[108:109]
	v_lshl_add_u64 v[52:53], v[74:75], 0, v[52:53]
	v_mul_f32_e32 v55, 0x45800000, v54
	v_cndmask_b32_e64 v54, v54, v55, s[8:9]
	v_pk_mul_f32 v[44:45], v[44:45], v[54:55] op_sel_hi:[1,0]
	v_pk_mul_f32 v[46:47], v[46:47], v[54:55] op_sel_hi:[1,0]
	v_pk_mul_f32 v[40:41], v[40:41], v[54:55] op_sel_hi:[1,0]
	v_pk_mul_f32 v[42:43], v[42:43], v[54:55] op_sel_hi:[1,0]
	v_pk_mul_f32 v[44:45], v[160:161], v[44:45]
	v_pk_mul_f32 v[46:47], v[162:163], v[46:47]
	v_cvt_pk_bf16_f32 v44, v44, v45
	v_cvt_pk_bf16_f32 v45, v46, v47
	global_store_dwordx2 v[52:53], v[44:45], off
	v_pk_mul_f32 v[36:37], v[36:37], v[54:55] op_sel_hi:[1,0]
	v_pk_mul_f32 v[38:39], v[38:39], v[54:55] op_sel_hi:[1,0]
	v_pk_mul_f32 v[32:33], v[32:33], v[54:55] op_sel_hi:[1,0]
	v_pk_mul_f32 v[34:35], v[34:35], v[54:55] op_sel_hi:[1,0]
	v_pk_mul_f32 v[40:41], v[166:167], v[40:41]
	v_pk_mul_f32 v[42:43], v[42:43], v[168:169]
	v_cvt_pk_bf16_f32 v40, v40, v41
	v_cvt_pk_bf16_f32 v41, v42, v43
	global_store_dwordx2 v[52:53], v[40:41], off offset:512
	v_pk_mul_f32 v[36:37], v[36:37], v[170:171]
	v_pk_mul_f32 v[38:39], v[38:39], v[172:173]
	v_cvt_pk_bf16_f32 v36, v36, v37
	v_cvt_pk_bf16_f32 v37, v38, v39
	global_store_dwordx2 v[52:53], v[36:37], off offset:1024
	v_pk_mul_f32 v[32:33], v[32:33], v[174:175]
	v_pk_mul_f32 v[34:35], v[34:35], v[176:177]
	v_cvt_pk_bf16_f32 v32, v32, v33
	v_cvt_pk_bf16_f32 v33, v34, v35
	global_store_dwordx2 v[52:53], v[32:33], off offset:1536
	s_or_b64 exec, exec, s[10:11]
	s_and_saveexec_b64 s[8:9], s[6:7]
	s_cbranch_execz .LBB0_96
.LBB0_98:
	ds_bpermute_b32 v36, v124, v89
	v_ashrrev_i32_e32 v97, 31, v96
	v_lshlrev_b32_e32 v38, 16, v107
	s_waitcnt lgkmcnt(0)
	v_add_f32_e32 v36, v89, v36
	ds_bpermute_b32 v37, v125, v36
	s_waitcnt lgkmcnt(0)
	v_add_f32_e32 v36, v36, v37
	ds_bpermute_b32 v37, v126, v36
	s_waitcnt lgkmcnt(0)
	v_add_f32_e32 v36, v36, v37
	ds_bpermute_b32 v37, v127, v36
	s_waitcnt lgkmcnt(0)
	v_add_f32_e32 v36, v36, v37
	ds_bpermute_b32 v37, v128, v36
	s_waitcnt lgkmcnt(0)
	v_add_f32_e32 v39, v36, v37
	ds_bpermute_b32 v40, v129, v39
	v_lshlrev_b32_e32 v36, 16, v106
	v_and_b32_e32 v37, 0xffff0000, v106
	s_waitcnt lgkmcnt(0)
	v_add_f32_e32 v39, v39, v40
	v_fmamk_f32 v39, v39, 0x3a800000, v198
	v_mul_f32_e32 v40, 0x4b800000, v39
	v_cmp_gt_f32_e64 s[6:7], s51, v39
	s_nop 1
	v_cndmask_b32_e64 v39, v39, v40, s[6:7]
	v_rsq_f32_e32 v42, v39
	v_and_b32_e32 v39, 0xffff0000, v107
	v_lshlrev_b64 v[40:41], 12, v[96:97]
	v_lshl_add_u64 v[40:41], v[70:71], 0, v[40:41]
	v_mul_f32_e32 v43, 0x45800000, v42
	v_cndmask_b32_e64 v42, v42, v43, s[6:7]
	v_pk_mul_f32 v[36:37], v[42:43], v[36:37] op_sel_hi:[0,1]
	v_pk_mul_f32 v[38:39], v[42:43], v[38:39] op_sel_hi:[0,1]
	v_pk_fma_f32 v[28:29], v[142:143], v[36:37], v[28:29]
	v_pk_fma_f32 v[30:31], v[144:145], v[38:39], v[30:31]
	global_store_dwordx4 v[40:41], v[28:31], off
	v_lshlrev_b32_e32 v36, 16, v104
	v_and_b32_e32 v37, 0xffff0000, v104
	v_lshlrev_b32_e32 v38, 16, v105
	v_and_b32_e32 v39, 0xffff0000, v105
	v_pk_mul_f32 v[36:37], v[42:43], v[36:37] op_sel_hi:[0,1]
	v_pk_mul_f32 v[38:39], v[42:43], v[38:39] op_sel_hi:[0,1]
	v_pk_fma_f32 v[24:25], v[36:37], v[146:147], v[24:25]
	v_pk_fma_f32 v[26:27], v[38:39], v[148:149], v[26:27]
	global_store_dwordx4 v[40:41], v[24:27], off offset:1024
	v_lshlrev_b32_e32 v36, 16, v102
	v_and_b32_e32 v37, 0xffff0000, v102
	v_lshlrev_b32_e32 v38, 16, v103
	v_and_b32_e32 v39, 0xffff0000, v103
	v_pk_mul_f32 v[36:37], v[42:43], v[36:37] op_sel_hi:[0,1]
	v_pk_mul_f32 v[38:39], v[42:43], v[38:39] op_sel_hi:[0,1]
	v_pk_fma_f32 v[20:21], v[36:37], v[152:153], v[20:21]
	v_pk_fma_f32 v[22:23], v[38:39], v[154:155], v[22:23]
	global_store_dwordx4 v[40:41], v[20:23], off offset:2048
	v_lshlrev_b32_e32 v36, 16, v100
	v_and_b32_e32 v37, 0xffff0000, v100
	v_lshlrev_b32_e32 v38, 16, v101
	v_and_b32_e32 v39, 0xffff0000, v101
	v_pk_mul_f32 v[36:37], v[42:43], v[36:37] op_sel_hi:[0,1]
	v_pk_mul_f32 v[38:39], v[42:43], v[38:39] op_sel_hi:[0,1]
	v_mov_b32_e32 v42, v31
	v_mov_b32_e32 v43, v27
	v_pk_fma_f32 v[16:17], v[36:37], v[156:157], v[16:17]
	v_pk_fma_f32 v[18:19], v[38:39], v[158:159], v[18:19]
	global_store_dwordx4 v[40:41], v[16:19], off offset:3072
	v_mov_b32_e32 v38, v29
	v_mov_b32_e32 v39, v25
	v_mov_b32_e32 v36, v28
	v_mov_b32_e32 v37, v24
	v_pk_mul_f32 v[38:39], v[38:39], v[38:39]
	v_mov_b32_e32 v40, v30
	v_mov_b32_e32 v41, v26
	v_pk_fma_f32 v[36:37], v[36:37], v[36:37], v[38:39]
	v_mov_b32_e32 v38, v21
	v_pk_fma_f32 v[36:37], v[40:41], v[40:41], v[36:37]
	v_mov_b32_e32 v39, v17
	v_pk_fma_f32 v[36:37], v[42:43], v[42:43], v[36:37]
	v_pk_mul_f32 v[38:39], v[38:39], v[38:39]
	v_add_f32_e32 v44, v36, v37
	v_mov_b32_e32 v36, v20
	v_mov_b32_e32 v37, v16
	v_mov_b32_e32 v40, v22
	v_mov_b32_e32 v41, v18
	v_pk_fma_f32 v[36:37], v[36:37], v[36:37], v[38:39]
	v_mov_b32_e32 v42, v23
	v_mov_b32_e32 v43, v19
	v_pk_fma_f32 v[36:37], v[40:41], v[40:41], v[36:37]
	s_nop 0
	v_pk_fma_f32 v[36:37], v[42:43], v[42:43], v[36:37]
	s_nop 0
	v_add_f32_e32 v36, v44, v36
	v_add_f32_e32 v36, v36, v37
	ds_bpermute_b32 v37, v124, v36
	s_waitcnt lgkmcnt(0)
	v_add_f32_e32 v36, v36, v37
	ds_bpermute_b32 v37, v125, v36
	s_waitcnt lgkmcnt(0)
	v_add_f32_e32 v36, v36, v37
	ds_bpermute_b32 v37, v126, v36
	s_waitcnt lgkmcnt(0)
	v_add_f32_e32 v36, v36, v37
	ds_bpermute_b32 v37, v127, v36
	s_waitcnt lgkmcnt(0)
	v_add_f32_e32 v36, v36, v37
	ds_bpermute_b32 v37, v128, v36
	s_waitcnt lgkmcnt(0)
	v_add_f32_e32 v36, v36, v37
	ds_bpermute_b32 v37, v129, v36
	s_waitcnt lgkmcnt(0)
	v_add_f32_e32 v36, v36, v37
	v_fmamk_f32 v36, v36, 0x3a800000, v198
	v_mul_f32_e32 v37, 0x4b800000, v36
	v_cmp_gt_f32_e64 s[6:7], s51, v36
	s_nop 1
	v_cndmask_b32_e64 v36, v36, v37, s[6:7]
	v_rsq_f32_e32 v38, v36
	v_lshlrev_b64 v[36:37], 11, v[96:97]
	v_lshl_add_u64 v[36:37], v[74:75], 0, v[36:37]
	v_mul_f32_e32 v39, 0x45800000, v38
	v_cndmask_b32_e64 v38, v38, v39, s[6:7]
	v_pk_mul_f32 v[28:29], v[28:29], v[38:39] op_sel_hi:[1,0]
	v_pk_mul_f32 v[30:31], v[30:31], v[38:39] op_sel_hi:[1,0]
	v_pk_mul_f32 v[24:25], v[24:25], v[38:39] op_sel_hi:[1,0]
	v_pk_mul_f32 v[26:27], v[26:27], v[38:39] op_sel_hi:[1,0]
	v_pk_mul_f32 v[28:29], v[160:161], v[28:29]
	v_pk_mul_f32 v[30:31], v[162:163], v[30:31]
	v_cvt_pk_bf16_f32 v28, v28, v29
	v_cvt_pk_bf16_f32 v29, v30, v31
	global_store_dwordx2 v[36:37], v[28:29], off
	v_pk_mul_f32 v[20:21], v[20:21], v[38:39] op_sel_hi:[1,0]
	v_pk_mul_f32 v[22:23], v[22:23], v[38:39] op_sel_hi:[1,0]
	v_pk_mul_f32 v[16:17], v[16:17], v[38:39] op_sel_hi:[1,0]
	v_pk_mul_f32 v[18:19], v[18:19], v[38:39] op_sel_hi:[1,0]
	v_pk_mul_f32 v[24:25], v[166:167], v[24:25]
	v_pk_mul_f32 v[26:27], v[26:27], v[168:169]
	v_cvt_pk_bf16_f32 v24, v24, v25
	v_cvt_pk_bf16_f32 v25, v26, v27
	global_store_dwordx2 v[36:37], v[24:25], off offset:512
	v_pk_mul_f32 v[20:21], v[20:21], v[170:171]
	v_pk_mul_f32 v[22:23], v[22:23], v[172:173]
	v_cvt_pk_bf16_f32 v20, v20, v21
	v_cvt_pk_bf16_f32 v21, v22, v23
	global_store_dwordx2 v[36:37], v[20:21], off offset:1024
	v_pk_mul_f32 v[16:17], v[16:17], v[174:175]
	v_pk_mul_f32 v[18:19], v[18:19], v[176:177]
	v_cvt_pk_bf16_f32 v16, v16, v17
	v_cvt_pk_bf16_f32 v17, v18, v19
	global_store_dwordx2 v[36:37], v[16:17], off offset:1536
	s_or_b64 exec, exec, s[8:9]
	s_and_saveexec_b64 s[6:7], s[4:5]
	s_cbranch_execz .LBB0_85
.LBB0_99:
	s_waitcnt vmcnt(0)
	ds_bpermute_b32 v20, v124, v65
	v_ashrrev_i32_e32 v89, 31, v88
	v_lshlrev_b32_e32 v22, 16, v99
	s_waitcnt lgkmcnt(0)
	v_add_f32_e32 v20, v65, v20
	ds_bpermute_b32 v21, v125, v20
	s_waitcnt lgkmcnt(0)
	v_add_f32_e32 v20, v20, v21
	ds_bpermute_b32 v21, v126, v20
	s_waitcnt lgkmcnt(0)
	v_add_f32_e32 v20, v20, v21
	ds_bpermute_b32 v21, v127, v20
	s_waitcnt lgkmcnt(0)
	v_add_f32_e32 v20, v20, v21
	ds_bpermute_b32 v21, v128, v20
	s_waitcnt lgkmcnt(0)
	v_add_f32_e32 v23, v20, v21
	ds_bpermute_b32 v24, v129, v23
	v_lshlrev_b32_e32 v20, 16, v98
	v_and_b32_e32 v21, 0xffff0000, v98
	s_waitcnt lgkmcnt(0)
	v_add_f32_e32 v23, v23, v24
	v_fmamk_f32 v23, v23, 0x3a800000, v198
	v_mul_f32_e32 v24, 0x4b800000, v23
	v_cmp_gt_f32_e64 s[4:5], s51, v23
	s_nop 1
	v_cndmask_b32_e64 v23, v23, v24, s[4:5]
	v_rsq_f32_e32 v26, v23
	v_and_b32_e32 v23, 0xffff0000, v99
	v_lshlrev_b64 v[24:25], 12, v[88:89]
	v_lshl_add_u64 v[24:25], v[70:71], 0, v[24:25]
	v_mul_f32_e32 v27, 0x45800000, v26
	v_cndmask_b32_e64 v26, v26, v27, s[4:5]
	v_pk_mul_f32 v[20:21], v[26:27], v[20:21] op_sel_hi:[0,1]
	v_pk_mul_f32 v[22:23], v[26:27], v[22:23] op_sel_hi:[0,1]
	v_pk_fma_f32 v[12:13], v[142:143], v[20:21], v[12:13]
	v_pk_fma_f32 v[14:15], v[144:145], v[22:23], v[14:15]
	global_store_dwordx4 v[24:25], v[12:15], off
	v_lshlrev_b32_e32 v20, 16, v94
	v_and_b32_e32 v21, 0xffff0000, v94
	v_lshlrev_b32_e32 v22, 16, v95
	v_and_b32_e32 v23, 0xffff0000, v95
	v_pk_mul_f32 v[20:21], v[26:27], v[20:21] op_sel_hi:[0,1]
	v_pk_mul_f32 v[22:23], v[26:27], v[22:23] op_sel_hi:[0,1]
	v_pk_fma_f32 v[8:9], v[20:21], v[146:147], v[8:9]
	v_pk_fma_f32 v[10:11], v[22:23], v[148:149], v[10:11]
	global_store_dwordx4 v[24:25], v[8:11], off offset:1024
	v_lshlrev_b32_e32 v20, 16, v92
	v_and_b32_e32 v21, 0xffff0000, v92
	v_lshlrev_b32_e32 v22, 16, v93
	v_and_b32_e32 v23, 0xffff0000, v93
	v_pk_mul_f32 v[20:21], v[26:27], v[20:21] op_sel_hi:[0,1]
	v_pk_mul_f32 v[22:23], v[26:27], v[22:23] op_sel_hi:[0,1]
	v_pk_fma_f32 v[4:5], v[20:21], v[152:153], v[4:5]
	v_pk_fma_f32 v[6:7], v[22:23], v[154:155], v[6:7]
	global_store_dwordx4 v[24:25], v[4:7], off offset:2048
	v_lshlrev_b32_e32 v20, 16, v90
	v_and_b32_e32 v21, 0xffff0000, v90
	v_lshlrev_b32_e32 v22, 16, v91
	v_and_b32_e32 v23, 0xffff0000, v91
	v_pk_mul_f32 v[20:21], v[26:27], v[20:21] op_sel_hi:[0,1]
	v_pk_mul_f32 v[22:23], v[26:27], v[22:23] op_sel_hi:[0,1]
	v_mov_b32_e32 v26, v15
	v_mov_b32_e32 v27, v11
	v_pk_fma_f32 v[0:1], v[20:21], v[156:157], v[0:1]
	v_pk_fma_f32 v[2:3], v[22:23], v[158:159], v[2:3]
	global_store_dwordx4 v[24:25], v[0:3], off offset:3072
	v_mov_b32_e32 v22, v13
	v_mov_b32_e32 v23, v9
	v_mov_b32_e32 v20, v12
	v_mov_b32_e32 v21, v8
	v_pk_mul_f32 v[22:23], v[22:23], v[22:23]
	v_mov_b32_e32 v24, v14
	v_mov_b32_e32 v25, v10
	v_pk_fma_f32 v[20:21], v[20:21], v[20:21], v[22:23]
	v_mov_b32_e32 v22, v5
	v_pk_fma_f32 v[20:21], v[24:25], v[24:25], v[20:21]
	v_mov_b32_e32 v23, v1
	v_pk_fma_f32 v[20:21], v[26:27], v[26:27], v[20:21]
	v_pk_mul_f32 v[22:23], v[22:23], v[22:23]
	v_add_f32_e32 v28, v20, v21
	v_mov_b32_e32 v20, v4
	v_mov_b32_e32 v21, v0
	v_mov_b32_e32 v24, v6
	v_mov_b32_e32 v25, v2
	v_pk_fma_f32 v[20:21], v[20:21], v[20:21], v[22:23]
	v_mov_b32_e32 v26, v7
	v_mov_b32_e32 v27, v3
	v_pk_fma_f32 v[20:21], v[24:25], v[24:25], v[20:21]
	s_nop 0
	v_pk_fma_f32 v[20:21], v[26:27], v[26:27], v[20:21]
	s_nop 0
	v_add_f32_e32 v20, v28, v20
	v_add_f32_e32 v20, v20, v21
	ds_bpermute_b32 v21, v124, v20
	s_waitcnt lgkmcnt(0)
	v_add_f32_e32 v20, v20, v21
	ds_bpermute_b32 v21, v125, v20
	s_waitcnt lgkmcnt(0)
	v_add_f32_e32 v20, v20, v21
	ds_bpermute_b32 v21, v126, v20
	s_waitcnt lgkmcnt(0)
	v_add_f32_e32 v20, v20, v21
	ds_bpermute_b32 v21, v127, v20
	s_waitcnt lgkmcnt(0)
	v_add_f32_e32 v20, v20, v21
	ds_bpermute_b32 v21, v128, v20
	s_waitcnt lgkmcnt(0)
	v_add_f32_e32 v20, v20, v21
	ds_bpermute_b32 v21, v129, v20
	s_waitcnt lgkmcnt(0)
	v_add_f32_e32 v20, v20, v21
	v_fmamk_f32 v20, v20, 0x3a800000, v198
	v_mul_f32_e32 v21, 0x4b800000, v20
	v_cmp_gt_f32_e64 s[4:5], s51, v20
	s_nop 1
	v_cndmask_b32_e64 v20, v20, v21, s[4:5]
	v_rsq_f32_e32 v22, v20
	v_lshlrev_b64 v[20:21], 11, v[88:89]
	v_lshl_add_u64 v[20:21], v[74:75], 0, v[20:21]
	v_mul_f32_e32 v23, 0x45800000, v22
	v_cndmask_b32_e64 v22, v22, v23, s[4:5]
	v_pk_mul_f32 v[12:13], v[12:13], v[22:23] op_sel_hi:[1,0]
	v_pk_mul_f32 v[14:15], v[14:15], v[22:23] op_sel_hi:[1,0]
	v_pk_mul_f32 v[8:9], v[8:9], v[22:23] op_sel_hi:[1,0]
	v_pk_mul_f32 v[10:11], v[10:11], v[22:23] op_sel_hi:[1,0]
	v_pk_mul_f32 v[12:13], v[160:161], v[12:13]
	v_pk_mul_f32 v[14:15], v[162:163], v[14:15]
	v_cvt_pk_bf16_f32 v12, v12, v13
	v_cvt_pk_bf16_f32 v13, v14, v15
	global_store_dwordx2 v[20:21], v[12:13], off
	v_pk_mul_f32 v[4:5], v[4:5], v[22:23] op_sel_hi:[1,0]
	v_pk_mul_f32 v[6:7], v[6:7], v[22:23] op_sel_hi:[1,0]
	v_pk_mul_f32 v[0:1], v[0:1], v[22:23] op_sel_hi:[1,0]
	v_pk_mul_f32 v[2:3], v[2:3], v[22:23] op_sel_hi:[1,0]
	v_pk_mul_f32 v[8:9], v[166:167], v[8:9]
	v_pk_mul_f32 v[10:11], v[10:11], v[168:169]
	v_cvt_pk_bf16_f32 v8, v8, v9
	v_cvt_pk_bf16_f32 v9, v10, v11
	global_store_dwordx2 v[20:21], v[8:9], off offset:512
	v_pk_mul_f32 v[4:5], v[4:5], v[170:171]
	v_pk_mul_f32 v[6:7], v[6:7], v[172:173]
	v_cvt_pk_bf16_f32 v4, v4, v5
	v_cvt_pk_bf16_f32 v5, v6, v7
	global_store_dwordx2 v[20:21], v[4:5], off offset:1024
	v_pk_mul_f32 v[0:1], v[0:1], v[174:175]
	v_pk_mul_f32 v[2:3], v[2:3], v[176:177]
	v_cvt_pk_bf16_f32 v0, v0, v1
	v_cvt_pk_bf16_f32 v1, v2, v3
	global_store_dwordx2 v[20:21], v[0:1], off offset:1536
	s_branch .LBB0_85
